# filter-table stores transposed through LDS (position-contiguous 64B runs instead of 2-byte channel scatter)
# speedup vs baseline: 1.1077x; 1.0342x over previous
; #define MFMA(a, b, c) __builtin_amdgcn_mfma_f32_32x32x16_bf16((a), (b), (c), 0, 0, 0)
; DI f32x16 zero16() { f32x16 z; for (int i = 0; i < 16; ++i) z[i] = 0.f; return z; }
; DI void filter_tile(const P& p, int l, int tile, char* smem) {
;     ...
;   for (int nb = 0; nb < 8; nb += 2) {
;     u32x4 bw[2][4];
; #pragma unroll
;     for (int u = 0; u < 2; ++u) {
;       const int col = wave * 256 + (nb + u) * 32 + li;
; #pragma unroll
;       for (int ks = 0; ks < 4; ++ks) {
;         const float* wp = w4 + (size_t)(16 * ks + 8 * g) * 2048 + col;
;         const float a0 = wp[0], a1 = wp[2048], a2 = wp[2 * 2048], a3 = wp[3 * 2048];
;         const float a4 = wp[4 * 2048], a5 = wp[5 * 2048], a6 = wp[6 * 2048], a7 = wp[7 * 2048];
;         u32x4 t; t[0] = pack2(a0, a1); t[1] = pack2(a2, a3); t[2] = pack2(a4, a5); t[3] = pack2(a6, a7);
;         bw[u][ks] = t;
;       }
;     }
; #pragma unroll
;     for (int u = 0; u < 2; ++u) {
;       const int col = wave * 256 + (nb + u) * 32 + li;
;       f32x16 acc = zero16();
; #pragma unroll
;       for (int ks = 0; ks < 4; ++ks) acc = MFMA(af[ks], __builtin_bit_cast(bf16x8, bw[u][ks]), acc);
.LBB0_183:
	v_lshrrev_b32_e32 v241, 6, v198
	v_mul_u32_u24_e32 v241, 0x900, v241
	v_add_u32_e32 v241, 0x10000, v241
	v_and_b32_e32 v242, 31, v198
	v_bfe_u32 v243, v198, 5, 1
	v_mul_u32_u24_e32 v222, 0x44, v242
	v_lshl_add_u32 v222, v243, 3, v222
	v_add_u32_e32 v222, v222, v241
	v_mul_u32_u24_e32 v223, 0x44, v243
	v_lshl_add_u32 v223, v242, 1, v223
	v_add_u32_e32 v223, v223, v241
	v_add_u32_e32 v244, s64, v242
	v_sub_u32_e32 v245, 0x2000, v244
	v_add_u32_e32 v244, 0x2000, v244
	v_cndmask_b32_e64 v244, v245, v244, s[6:7]
	v_lshlrev_b32_e32 v244, 1, v244
	v_lshl_add_u32 v240, v243, 15, v244
	v_ashrrev_i32_e32 v77, 31, v76
	v_lshl_add_u64 v[4:5], v[76:77], 2, s[70:71]
	v_lshl_add_u64 v[84:85], v[40:41], 2, v[4:5]
	v_add_co_u32_e32 v86, vcc, 0x2000, v84
	s_waitcnt lgkmcnt(0)
	v_lshl_add_u64 v[0:1], v[4:5], 0, v[78:79]
	v_addc_co_u32_e32 v87, vcc, 0, v85, vcc
	v_add_co_u32_e32 v88, vcc, 0x4000, v84
	global_load_dword v90, v[0:1], off
	s_nop 0
	v_addc_co_u32_e32 v89, vcc, 0, v85, vcc
	v_add_co_u32_e32 v6, vcc, 0x6000, v84
	global_load_dword v32, v[84:85], off
	s_nop 0
	v_addc_co_u32_e32 v7, vcc, 0, v85, vcc
	v_add_co_u32_e32 v8, vcc, 0x8000, v84
	global_load_dword v35, v[6:7], off
	s_nop 0
	v_addc_co_u32_e32 v9, vcc, 0, v85, vcc
	v_add_co_u32_e32 v12, vcc, 0xa000, v84
	global_load_dword v36, v[8:9], off
	s_nop 0
	v_addc_co_u32_e32 v13, vcc, 0, v85, vcc
	v_add_co_u32_e32 v14, vcc, 0xc000, v84
	global_load_dword v37, v[12:13], off
	s_nop 0
	v_addc_co_u32_e32 v15, vcc, 0, v85, vcc
	v_add_co_u32_e32 v10, vcc, 0xe000, v84
	global_load_dword v38, v[14:15], off
	s_nop 0
	v_addc_co_u32_e32 v11, vcc, 0, v85, vcc
	v_add_co_u32_e32 v2, vcc, s65, v0
	global_load_dword v39, v[10:11], off
	s_nop 0
	v_addc_co_u32_e32 v3, vcc, 0, v1, vcc
	global_load_dword v91, v[2:3], off
	v_add_co_u32_e32 v2, vcc, s61, v0
	global_load_dword v33, v[86:87], off
	s_nop 0
	v_addc_co_u32_e32 v3, vcc, 0, v1, vcc
	global_load_dword v92, v[2:3], off
	v_add_co_u32_e32 v2, vcc, s2, v0
	global_load_dword v34, v[88:89], off
	s_nop 0
	v_addc_co_u32_e32 v3, vcc, 0, v1, vcc
	global_load_dword v93, v[2:3], off
	v_add_co_u32_e32 v2, vcc, s1, v0
	s_nop 1
	v_addc_co_u32_e32 v3, vcc, 0, v1, vcc
	global_load_dword v94, v[2:3], off
	v_add_co_u32_e32 v2, vcc, s62, v0
	s_nop 1
	v_addc_co_u32_e32 v3, vcc, 0, v1, vcc
	global_load_dword v95, v[2:3], off
	v_add_co_u32_e32 v2, vcc, s63, v0
	s_nop 1
	v_addc_co_u32_e32 v3, vcc, 0, v1, vcc
	v_add_co_u32_e32 v0, vcc, s33, v0
	global_load_dword v96, v[2:3], off
	s_nop 0
	v_addc_co_u32_e32 v1, vcc, 0, v1, vcc
	global_load_dword v97, v[0:1], off
	v_lshl_add_u64 v[0:1], v[4:5], 0, v[80:81]
	v_add_co_u32_e32 v2, vcc, s65, v0
	global_load_dword v98, v[0:1], off
	s_nop 0
	v_addc_co_u32_e32 v3, vcc, 0, v1, vcc
	global_load_dword v99, v[2:3], off
	v_add_co_u32_e32 v2, vcc, s61, v0
	s_nop 1
	v_addc_co_u32_e32 v3, vcc, 0, v1, vcc
	global_load_dword v100, v[2:3], off
	v_add_co_u32_e32 v2, vcc, s2, v0
	s_nop 1
	v_addc_co_u32_e32 v3, vcc, 0, v1, vcc
	global_load_dword v101, v[2:3], off
	v_add_co_u32_e32 v2, vcc, s1, v0
	s_nop 1
	v_addc_co_u32_e32 v3, vcc, 0, v1, vcc
	global_load_dword v102, v[2:3], off
	v_add_co_u32_e32 v2, vcc, s62, v0
	s_nop 1
	v_addc_co_u32_e32 v3, vcc, 0, v1, vcc
	global_load_dword v103, v[2:3], off
	v_add_co_u32_e32 v2, vcc, s63, v0
	s_nop 1
	v_addc_co_u32_e32 v3, vcc, 0, v1, vcc
	v_add_co_u32_e32 v0, vcc, s33, v0
	global_load_dword v104, v[2:3], off
	s_nop 0
	v_addc_co_u32_e32 v1, vcc, 0, v1, vcc
	global_load_dword v105, v[0:1], off
	s_waitcnt vmcnt(19)
	v_cvt_pk_bf16_f32 v2, v36, v37
	s_waitcnt vmcnt(17)
	v_cvt_pk_bf16_f32 v3, v38, v39
	s_waitcnt vmcnt(16)
	v_cvt_pk_bf16_f32 v36, v90, v91
	s_waitcnt vmcnt(15)
	v_cvt_pk_bf16_f32 v0, v32, v33
	s_waitcnt vmcnt(13)
	v_cvt_pk_bf16_f32 v1, v34, v35
	s_waitcnt vmcnt(12)
	v_cvt_pk_bf16_f32 v37, v92, v93
	s_waitcnt vmcnt(10)
	v_cvt_pk_bf16_f32 v38, v94, v95
	s_waitcnt vmcnt(8)
	v_cvt_pk_bf16_f32 v39, v96, v97
	s_waitcnt vmcnt(6)
	v_cvt_pk_bf16_f32 v32, v98, v99
	v_lshl_add_u64 v[98:99], v[4:5], 0, v[82:83]
	v_add_co_u32_e32 v90, vcc, s65, v98
	global_load_dword v92, v[98:99], off
	s_nop 0
	v_addc_co_u32_e32 v91, vcc, 0, v99, vcc
	global_load_dword v94, v[90:91], off
	v_add_co_u32_e32 v90, vcc, s61, v98
	v_lshl_add_u64 v[4:5], v[4:5], 0, s[58:59]
	s_nop 0
	v_addc_co_u32_e32 v91, vcc, 0, v99, vcc
	global_load_dword v96, v[90:91], off
	v_add_co_u32_e32 v90, vcc, s2, v98
	s_waitcnt vmcnt(7)
	v_cvt_pk_bf16_f32 v33, v100, v101
	v_addc_co_u32_e32 v91, vcc, 0, v99, vcc
	global_load_dword v97, v[90:91], off
	v_add_co_u32_e32 v90, vcc, s1, v98
	s_waitcnt vmcnt(6)
	v_cvt_pk_bf16_f32 v34, v102, v103
	v_addc_co_u32_e32 v91, vcc, 0, v99, vcc
	v_add_co_u32_e32 v100, vcc, s62, v98
	global_load_dword v90, v[90:91], off
	s_nop 0
	v_addc_co_u32_e32 v101, vcc, 0, v99, vcc
	global_load_dword v91, v[100:101], off
	v_add_co_u32_e32 v100, vcc, s63, v98
	s_waitcnt vmcnt(6)
; #define MFMA(a, b, c) __builtin_amdgcn_mfma_f32_32x32x16_bf16((a), (b), (c), 0, 0, 0)
; DI u16 f2bf(float a) { return (u16)(pack2(a, 0.f) & 0xffffu); }
; DI int crow(int reg, int g) { return (reg & 3) + 8 * (reg >> 2) + 4 * g; }
; DI f32x16 zero16() { f32x16 z; for (int i = 0; i < 16; ++i) z[i] = 0.f; return z; }
; DI void filter_tile(const P& p, int l, int tile, char* smem) {
;     ...
;     for (int u = 0; u < 2; ++u) {
;       const int col = wave * 256 + (nb + u) * 32 + li;
; #pragma unroll
;       for (int ks = 0; ks < 4; ++ks) {
;         const float* wp = w4 + (size_t)(16 * ks + 8 * g) * 2048 + col;
;         const float a0 = wp[0], a1 = wp[2048], a2 = wp[2 * 2048], a3 = wp[3 * 2048];
;         const float a4 = wp[4 * 2048], a5 = wp[5 * 2048], a6 = wp[6 * 2048], a7 = wp[7 * 2048];
;         u32x4 t; t[0] = pack2(a0, a1); t[1] = pack2(a2, a3); t[2] = pack2(a4, a5); t[3] = pack2(a6, a7);
;         bw[u][ks] = t;
;       }
;     }
; #pragma unroll
;     for (int u = 0; u < 2; ++u) {
;       const int col = wave * 256 + (nb + u) * 32 + li;
;       f32x16 acc = zero16();
; #pragma unroll
;       for (int ks = 0; ks < 4; ++ks) acc = MFMA(af[ks], __builtin_bit_cast(bf16x8, bw[u][ks]), acc);
;       const int j = col >> 9, c = col & 511;
;       const int order = j & 1;
;       const bool fwd = j < 2;
;       const float delta = fabsf(min_decay + (float)c * ((max_decay - min_decay) / 511.0f));
;       u16* tb = p.Tb + (size_t)(order * 512 + c) * 16384;
;       float asum = 0.f;
; #pragma unroll
;       for (int reg = 0; reg < 16; ++reg) {
;         const int m = m0 + crow(reg, g);
;         const float t = (float)m / 8191.0f;
;         const float v = acc[reg] * __expf(-t * delta);
;         if (fwd) { tb[8192 - m] = f2bf(v); asum += fabsf(v); }
;         else if (m >= 1) { tb[8192 + m] = f2bf(v); asum += fabsf(v); }
	v_cvt_pk_bf16_f32 v35, v104, v105
	v_addc_co_u32_e32 v101, vcc, 0, v99, vcc
	v_add_co_u32_e32 v98, vcc, s33, v98
	global_load_dword v93, v[100:101], off
	s_nop 0
	v_addc_co_u32_e32 v99, vcc, 0, v99, vcc
	global_load_dword v95, v[98:99], off
	global_load_dword v112, v[84:85], off offset:128
	global_load_dword v113, v[86:87], off offset:128
	global_load_dword v115, v[88:89], off offset:128
	global_load_dword v116, v[6:7], off offset:128
	global_load_dword v117, v[8:9], off offset:128
	global_load_dword v118, v[12:13], off offset:128
	global_load_dword v119, v[14:15], off offset:128
	global_load_dword v120, v[10:11], off offset:128
	v_lshl_add_u64 v[6:7], v[4:5], 0, v[78:79]
	v_add_co_u32_e32 v8, vcc, s65, v6
	global_load_dword v121, v[6:7], off
	s_nop 0
	v_addc_co_u32_e32 v9, vcc, 0, v7, vcc
	global_load_dword v122, v[8:9], off
	v_add_co_u32_e32 v8, vcc, s61, v6
	v_lshl_add_u64 v[84:85], v[4:5], 0, v[82:83]
	s_nop 0
	v_addc_co_u32_e32 v9, vcc, 0, v7, vcc
	global_load_dword v123, v[8:9], off
	v_add_co_u32_e32 v8, vcc, s2, v6
	global_load_dword v137, v[84:85], off
	s_nop 0
	v_addc_co_u32_e32 v9, vcc, 0, v7, vcc
	global_load_dword v124, v[8:9], off
	v_add_co_u32_e32 v8, vcc, s1, v6
	s_nop 1
	v_addc_co_u32_e32 v9, vcc, 0, v7, vcc
	global_load_dword v125, v[8:9], off
	v_add_co_u32_e32 v8, vcc, s62, v6
	s_nop 1
	v_addc_co_u32_e32 v9, vcc, 0, v7, vcc
	global_load_dword v126, v[8:9], off
	v_add_co_u32_e32 v8, vcc, s63, v6
	s_nop 1
	v_addc_co_u32_e32 v9, vcc, 0, v7, vcc
	v_add_co_u32_e32 v6, vcc, s33, v6
	global_load_dword v127, v[8:9], off
	s_nop 0
	v_addc_co_u32_e32 v7, vcc, 0, v7, vcc
	global_load_dword v128, v[6:7], off
	v_lshl_add_u64 v[6:7], v[4:5], 0, v[80:81]
	v_add_co_u32_e32 v8, vcc, s65, v6
	global_load_dword v129, v[6:7], off
	s_nop 0
	v_addc_co_u32_e32 v9, vcc, 0, v7, vcc
	global_load_dword v130, v[8:9], off
	v_add_co_u32_e32 v8, vcc, s61, v6
	s_nop 1
	v_addc_co_u32_e32 v9, vcc, 0, v7, vcc
	global_load_dword v131, v[8:9], off
	v_add_co_u32_e32 v8, vcc, s2, v6
	s_nop 1
	v_addc_co_u32_e32 v9, vcc, 0, v7, vcc
	global_load_dword v132, v[8:9], off
	v_add_co_u32_e32 v8, vcc, s1, v6
	s_nop 1
	v_addc_co_u32_e32 v9, vcc, 0, v7, vcc
	global_load_dword v133, v[8:9], off
	v_add_co_u32_e32 v8, vcc, s62, v6
	s_nop 1
	v_addc_co_u32_e32 v9, vcc, 0, v7, vcc
	global_load_dword v134, v[8:9], off
	v_add_co_u32_e32 v8, vcc, s63, v6
	s_nop 1
	v_addc_co_u32_e32 v9, vcc, 0, v7, vcc
	v_add_co_u32_e32 v6, vcc, s33, v6
	global_load_dword v135, v[8:9], off
	s_nop 0
	v_addc_co_u32_e32 v7, vcc, 0, v7, vcc
	v_add_co_u32_e32 v4, vcc, s65, v84
	global_load_dword v136, v[6:7], off
	s_nop 0
	v_addc_co_u32_e32 v5, vcc, 0, v85, vcc
	global_load_dword v138, v[4:5], off
	v_add_co_u32_e32 v4, vcc, s61, v84
	s_nop 1
	v_addc_co_u32_e32 v5, vcc, 0, v85, vcc
	global_load_dword v139, v[4:5], off
	v_add_co_u32_e32 v4, vcc, s2, v84
	s_nop 1
	v_addc_co_u32_e32 v5, vcc, 0, v85, vcc
	global_load_dword v141, v[4:5], off
	v_add_co_u32_e32 v4, vcc, s1, v84
	s_nop 1
	v_addc_co_u32_e32 v5, vcc, 0, v85, vcc
	v_add_co_u32_e32 v86, vcc, s62, v84
	global_load_dword v140, v[4:5], off
	s_nop 0
	v_addc_co_u32_e32 v87, vcc, 0, v85, vcc
	global_load_dword v142, v[86:87], off
	s_waitcnt lgkmcnt(3)
	v_mfma_f32_32x32x16_bf16 v[0:15], v[16:19], v[0:3], 0
	v_add_co_u32_e32 v86, vcc, s63, v84
	s_nop 1
	v_addc_co_u32_e32 v87, vcc, 0, v85, vcc
	global_load_dword v143, v[86:87], off
	s_waitcnt lgkmcnt(2)
	v_mfma_f32_32x32x16_bf16 v[0:15], v[20:23], v[36:39], v[0:15]
	v_add_co_u32_e32 v36, vcc, s33, v84
	s_nop 1
	v_addc_co_u32_e32 v37, vcc, 0, v85, vcc
	global_load_dword v144, v[36:37], off
	v_and_b32_e32 v37, 0x1df, v76
	s_waitcnt lgkmcnt(1)
	v_mfma_f32_32x32x16_bf16 v[0:15], v[24:27], v[32:35], v[0:15]
	v_cvt_f32_u32_e32 v36, v37
	s_waitcnt vmcnt(38)
	v_cvt_pk_bf16_f32 v32, v92, v94
	s_waitcnt vmcnt(36)
	v_cvt_pk_bf16_f32 v33, v96, v97
	s_waitcnt vmcnt(34)
	v_cvt_pk_bf16_f32 v34, v90, v91
	s_waitcnt vmcnt(32)
	v_cvt_pk_bf16_f32 v35, v93, v95
	v_fmamk_f32 v36, v36, 0xbcc4df2d, v201
	s_waitcnt lgkmcnt(0)
	v_mfma_f32_32x32x16_bf16 v[0:15], v[28:31], v[32:35], v[0:15]
	v_mul_f32_e64 v32, v47, |v36|
	v_mul_f32_e32 v32, 0x3fb8aa3b, v32
	v_exp_f32_e32 v32, v32
	v_or_b32_e32 v33, v37, v43
	v_lshlrev_b32_e32 v188, 15, v33
	v_lshl_add_u64 v[34:35], s[44:45], 0, v[188:189]
	s_nop 5
	v_mul_f32_e32 v32, v32, v0
	v_and_b32_e32 v0, 0x7fffffff, v32
	s_and_saveexec_b64 s[78:79], s[6:7]
	s_xor_b64 s[78:79], exec, s[78:79]
	s_cbranch_execz .LBB0_187
	v_mov_b32_e32 v0, 0
	s_and_saveexec_b64 s[80:81], s[10:11]
	s_cbranch_execz .LBB0_186
	v_lshlrev_b32_e32 v188, 1, v42
	v_lshl_add_u64 v[38:39], v[34:35], 0, v[188:189]
	v_and_b32_e32 v0, 0x7fffffff, v32
	v_cvt_pk_bf16_f32 v37, v32, s0
	v_add_co_u32_e32 v32, vcc, 0x4000, v38
	s_nop 1
	v_addc_co_u32_e32 v33, vcc, 0, v39, vcc
	ds_write_b16 v222, v37 offset:0

; DI u16 f2bf(float a) { return (u16)(pack2(a, 0.f) & 0xffffu); }
; DI int crow(int reg, int g) { return (reg & 3) + 8 * (reg >> 2) + 4 * g; }
; DI void filter_tile(const P& p, int l, int tile, char* smem) {
;     ...
; #pragma unroll
;       for (int reg = 0; reg < 16; ++reg) {
;         const int m = m0 + crow(reg, g);
;         const float t = (float)m / 8191.0f;
;         const float v = acc[reg] * __expf(-t * delta);
;         if (fwd) { tb[8192 - m] = f2bf(v); asum += fabsf(v); }
;         else if (m >= 1) { tb[8192 + m] = f2bf(v); asum += fabsf(v); }
;       }
.LBB0_187:
	s_or_saveexec_b64 s[78:79], s[78:79]
	v_lshlrev_b32_e32 v110, 1, v44
	s_xor_b64 exec, exec, s[78:79]
	s_cbranch_execz .LBB0_189
	v_mov_b32_e32 v111, v189
	v_cvt_pk_bf16_f32 v37, v32, s0
	v_lshl_add_u64 v[32:33], v[34:35], 0, v[110:111]
	ds_write_b16 v222, v37 offset:0
.LBB0_189:
	s_or_b64 exec, exec, s[78:79]
	v_mul_f32_e64 v32, v49, |v36|
	v_mul_f32_e32 v32, 0x3fb8aa3b, v32
	v_exp_f32_e32 v32, v32
	s_nop 0
	v_mul_f32_e32 v37, v32, v1
	v_and_b32_e32 v1, 0x7fffffff, v37
	v_lshlrev_b32_e32 v32, 1, v42
	s_and_saveexec_b64 s[78:79], s[6:7]
	s_xor_b64 s[78:79], exec, s[78:79]
	s_cbranch_execz .LBB0_191
	v_mov_b32_e32 v33, v189
	v_lshl_add_u64 v[38:39], v[34:35], 0, v[32:33]
	v_add_co_u32_e32 v38, vcc, 0x4000, v38
	v_cvt_pk_bf16_f32 v33, v37, s0
	s_nop 0
	v_addc_co_u32_e32 v39, vcc, 0, v39, vcc
	ds_write_b16 v222, v33 offset:2
.LBB0_191:
	s_or_saveexec_b64 s[78:79], s[78:79]
	v_lshlrev_b32_e32 v108, 1, v46
	s_xor_b64 exec, exec, s[78:79]
	s_cbranch_execz .LBB0_193
	v_mov_b32_e32 v109, v189
	v_cvt_pk_bf16_f32 v33, v37, s0
	v_lshl_add_u64 v[38:39], v[34:35], 0, v[108:109]
	ds_write_b16 v222, v33 offset:2
.LBB0_193:
	s_or_b64 exec, exec, s[78:79]
	v_mul_f32_e64 v33, v51, |v36|
	v_mul_f32_e32 v33, 0x3fb8aa3b, v33
	v_exp_f32_e32 v33, v33
	s_nop 0
	v_mul_f32_e32 v37, v33, v2
	v_and_b32_e32 v2, 0x7fffffff, v37
	s_and_saveexec_b64 s[78:79], s[6:7]
	s_xor_b64 s[78:79], exec, s[78:79]
	s_cbranch_execz .LBB0_195
	v_mov_b32_e32 v33, v189
	v_lshl_add_u64 v[38:39], v[34:35], 0, v[32:33]
	v_add_co_u32_e32 v38, vcc, 0x4000, v38
	v_cvt_pk_bf16_f32 v33, v37, s0
	s_nop 0
	v_addc_co_u32_e32 v39, vcc, 0, v39, vcc
	ds_write_b16 v222, v33 offset:4
.LBB0_195:
	s_or_saveexec_b64 s[78:79], s[78:79]
	v_lshlrev_b32_e32 v106, 1, v48
	s_xor_b64 exec, exec, s[78:79]
	s_cbranch_execz .LBB0_197
	v_mov_b32_e32 v107, v189
	v_cvt_pk_bf16_f32 v33, v37, s0
	v_lshl_add_u64 v[38:39], v[34:35], 0, v[106:107]
	ds_write_b16 v222, v33 offset:4
.LBB0_197:
	s_or_b64 exec, exec, s[78:79]
	v_mul_f32_e64 v33, v53, |v36|
	v_mul_f32_e32 v33, 0x3fb8aa3b, v33
	v_exp_f32_e32 v33, v33
	s_nop 0
	v_mul_f32_e32 v37, v33, v3
	v_and_b32_e32 v3, 0x7fffffff, v37
	s_and_saveexec_b64 s[78:79], s[6:7]
	s_xor_b64 s[78:79], exec, s[78:79]
	s_cbranch_execz .LBB0_199
	v_mov_b32_e32 v33, v189
	v_lshl_add_u64 v[38:39], v[34:35], 0, v[32:33]
	v_add_co_u32_e32 v38, vcc, 0x4000, v38
	v_cvt_pk_bf16_f32 v33, v37, s0
	s_nop 0
	v_addc_co_u32_e32 v39, vcc, 0, v39, vcc
	ds_write_b16 v222, v33 offset:6
.LBB0_199:
	s_or_saveexec_b64 s[78:79], s[78:79]
	v_lshlrev_b32_e32 v104, 1, v50
	s_xor_b64 exec, exec, s[78:79]
	s_cbranch_execz .LBB0_201
	v_mov_b32_e32 v105, v189
	v_cvt_pk_bf16_f32 v33, v37, s0
	v_lshl_add_u64 v[38:39], v[34:35], 0, v[104:105]
	ds_write_b16 v222, v33 offset:6
.LBB0_201:
	s_or_b64 exec, exec, s[78:79]
	v_mul_f32_e64 v33, v55, |v36|
	v_mul_f32_e32 v33, 0x3fb8aa3b, v33
	v_exp_f32_e32 v33, v33
	s_nop 0
	v_mul_f32_e32 v37, v33, v4
	v_and_b32_e32 v4, 0x7fffffff, v37
	s_and_saveexec_b64 s[78:79], s[6:7]
	s_xor_b64 s[78:79], exec, s[78:79]
	s_cbranch_execz .LBB0_203
	v_mov_b32_e32 v33, v189
	v_lshl_add_u64 v[38:39], v[34:35], 0, v[32:33]
	v_add_co_u32_e32 v38, vcc, 0x4000, v38
	v_cvt_pk_bf16_f32 v33, v37, s0
	s_nop 0
	v_addc_co_u32_e32 v39, vcc, 0, v39, vcc
	ds_write_b16 v222, v33 offset:16
.LBB0_203:
	s_or_saveexec_b64 s[78:79], s[78:79]
	v_lshlrev_b32_e32 v102, 1, v52
	s_xor_b64 exec, exec, s[78:79]
	s_cbranch_execz .LBB0_205
	v_mov_b32_e32 v103, v189
	v_cvt_pk_bf16_f32 v33, v37, s0
	v_lshl_add_u64 v[38:39], v[34:35], 0, v[102:103]
	ds_write_b16 v222, v33 offset:16
.LBB0_205:
	s_or_b64 exec, exec, s[78:79]
	v_mul_f32_e64 v33, v57, |v36|
	v_mul_f32_e32 v33, 0x3fb8aa3b, v33
	v_exp_f32_e32 v33, v33
	s_nop 0
	v_mul_f32_e32 v37, v33, v5
	v_and_b32_e32 v5, 0x7fffffff, v37
	s_and_saveexec_b64 s[78:79], s[6:7]
	s_xor_b64 s[78:79], exec, s[78:79]
	s_cbranch_execz .LBB0_207
	v_mov_b32_e32 v33, v189
	v_lshl_add_u64 v[38:39], v[34:35], 0, v[32:33]
	v_add_co_u32_e32 v38, vcc, 0x4000, v38
	v_cvt_pk_bf16_f32 v33, v37, s0
	s_nop 0
	v_addc_co_u32_e32 v39, vcc, 0, v39, vcc
	ds_write_b16 v222, v33 offset:18
.LBB0_207:
	s_or_saveexec_b64 s[78:79], s[78:79]
	v_lshlrev_b32_e32 v100, 1, v54
	s_xor_b64 exec, exec, s[78:79]
	s_cbranch_execz .LBB0_209
	v_mov_b32_e32 v101, v189
	v_cvt_pk_bf16_f32 v33, v37, s0
	v_lshl_add_u64 v[38:39], v[34:35], 0, v[100:101]
	ds_write_b16 v222, v33 offset:18
.LBB0_209:
	s_or_b64 exec, exec, s[78:79]
	v_mul_f32_e64 v33, v59, |v36|
	v_mul_f32_e32 v33, 0x3fb8aa3b, v33
	v_exp_f32_e32 v33, v33
	s_nop 0
	v_mul_f32_e32 v37, v33, v6
	v_and_b32_e32 v6, 0x7fffffff, v37
	s_and_saveexec_b64 s[78:79], s[6:7]
	s_xor_b64 s[78:79], exec, s[78:79]
	s_cbranch_execz .LBB0_211
	v_mov_b32_e32 v33, v189
	v_lshl_add_u64 v[38:39], v[34:35], 0, v[32:33]
	v_add_co_u32_e32 v38, vcc, 0x4000, v38
	v_cvt_pk_bf16_f32 v33, v37, s0
	s_nop 0
	v_addc_co_u32_e32 v39, vcc, 0, v39, vcc
	ds_write_b16 v222, v33 offset:20
.LBB0_211:
	s_or_saveexec_b64 s[78:79], s[78:79]
	v_lshlrev_b32_e32 v98, 1, v56
	s_xor_b64 exec, exec, s[78:79]
	s_cbranch_execz .LBB0_213
	v_mov_b32_e32 v99, v189
	v_cvt_pk_bf16_f32 v33, v37, s0
	v_lshl_add_u64 v[38:39], v[34:35], 0, v[98:99]
	ds_write_b16 v222, v33 offset:20
.LBB0_213:
	s_or_b64 exec, exec, s[78:79]
	v_mul_f32_e64 v33, v61, |v36|
	v_mul_f32_e32 v33, 0x3fb8aa3b, v33
	v_exp_f32_e32 v33, v33
	s_nop 0
	v_mul_f32_e32 v37, v33, v7
	v_and_b32_e32 v7, 0x7fffffff, v37
	s_and_saveexec_b64 s[78:79], s[6:7]
	s_xor_b64 s[78:79], exec, s[78:79]
	s_cbranch_execz .LBB0_215
	v_mov_b32_e32 v33, v189
	v_lshl_add_u64 v[38:39], v[34:35], 0, v[32:33]
	v_add_co_u32_e32 v38, vcc, 0x4000, v38
	v_cvt_pk_bf16_f32 v33, v37, s0
	s_nop 0
	v_addc_co_u32_e32 v39, vcc, 0, v39, vcc
	ds_write_b16 v222, v33 offset:22
; DI u16 f2bf(float a) { return (u16)(pack2(a, 0.f) & 0xffffu); }
; DI int crow(int reg, int g) { return (reg & 3) + 8 * (reg >> 2) + 4 * g; }
; DI void filter_tile(const P& p, int l, int tile, char* smem) {
;     ...
; #pragma unroll
;       for (int reg = 0; reg < 16; ++reg) {
;         const int m = m0 + crow(reg, g);
;         const float t = (float)m / 8191.0f;
;         const float v = acc[reg] * __expf(-t * delta);
;         if (fwd) { tb[8192 - m] = f2bf(v); asum += fabsf(v); }
;         else if (m >= 1) { tb[8192 + m] = f2bf(v); asum += fabsf(v); }
;       }
.LBB0_215:
	s_or_saveexec_b64 s[78:79], s[78:79]
	v_lshlrev_b32_e32 v96, 1, v58
	s_xor_b64 exec, exec, s[78:79]
	s_cbranch_execz .LBB0_217
	v_mov_b32_e32 v97, v189
	v_cvt_pk_bf16_f32 v33, v37, s0
	v_lshl_add_u64 v[38:39], v[34:35], 0, v[96:97]
	ds_write_b16 v222, v33 offset:22
.LBB0_217:
	s_or_b64 exec, exec, s[78:79]
	v_mul_f32_e64 v33, v63, |v36|
	v_mul_f32_e32 v33, 0x3fb8aa3b, v33
	v_exp_f32_e32 v33, v33
	s_nop 0
	v_mul_f32_e32 v37, v33, v8
	v_and_b32_e32 v8, 0x7fffffff, v37
	s_and_saveexec_b64 s[78:79], s[6:7]
	s_xor_b64 s[78:79], exec, s[78:79]
	s_cbranch_execz .LBB0_219
	v_mov_b32_e32 v33, v189
	v_lshl_add_u64 v[38:39], v[34:35], 0, v[32:33]
	v_add_co_u32_e32 v38, vcc, 0x4000, v38
	v_cvt_pk_bf16_f32 v33, v37, s0
	s_nop 0
	v_addc_co_u32_e32 v39, vcc, 0, v39, vcc
	ds_write_b16 v222, v33 offset:32
.LBB0_219:
	s_or_saveexec_b64 s[78:79], s[78:79]
	v_lshlrev_b32_e32 v94, 1, v60
	s_xor_b64 exec, exec, s[78:79]
	s_cbranch_execz .LBB0_221
	v_mov_b32_e32 v95, v189
	v_cvt_pk_bf16_f32 v33, v37, s0
	v_lshl_add_u64 v[38:39], v[34:35], 0, v[94:95]
	ds_write_b16 v222, v33 offset:32
.LBB0_221:
	s_or_b64 exec, exec, s[78:79]
	v_mul_f32_e64 v33, v65, |v36|
	v_mul_f32_e32 v33, 0x3fb8aa3b, v33
	v_exp_f32_e32 v33, v33
	s_nop 0
	v_mul_f32_e32 v37, v33, v9
	v_and_b32_e32 v9, 0x7fffffff, v37
	s_and_saveexec_b64 s[78:79], s[6:7]
	s_xor_b64 s[78:79], exec, s[78:79]
	s_cbranch_execz .LBB0_223
	v_mov_b32_e32 v33, v189
	v_lshl_add_u64 v[38:39], v[34:35], 0, v[32:33]
	v_add_co_u32_e32 v38, vcc, 0x4000, v38
	v_cvt_pk_bf16_f32 v33, v37, s0
	s_nop 0
	v_addc_co_u32_e32 v39, vcc, 0, v39, vcc
	ds_write_b16 v222, v33 offset:34
.LBB0_223:
	s_or_saveexec_b64 s[78:79], s[78:79]
	v_lshlrev_b32_e32 v92, 1, v62
	s_xor_b64 exec, exec, s[78:79]
	s_cbranch_execz .LBB0_225
	v_mov_b32_e32 v93, v189
	v_cvt_pk_bf16_f32 v33, v37, s0
	v_lshl_add_u64 v[38:39], v[34:35], 0, v[92:93]
	ds_write_b16 v222, v33 offset:34
.LBB0_225:
	s_or_b64 exec, exec, s[78:79]
	v_mul_f32_e64 v33, v67, |v36|
	v_mul_f32_e32 v33, 0x3fb8aa3b, v33
	v_exp_f32_e32 v33, v33
	s_nop 0
	v_mul_f32_e32 v37, v33, v10
	v_and_b32_e32 v10, 0x7fffffff, v37
	s_and_saveexec_b64 s[78:79], s[6:7]
	s_xor_b64 s[78:79], exec, s[78:79]
	s_cbranch_execz .LBB0_227
	v_mov_b32_e32 v33, v189
	v_lshl_add_u64 v[38:39], v[34:35], 0, v[32:33]
	v_add_co_u32_e32 v38, vcc, 0x4000, v38
	v_cvt_pk_bf16_f32 v33, v37, s0
	s_nop 0
	v_addc_co_u32_e32 v39, vcc, 0, v39, vcc
	ds_write_b16 v222, v33 offset:36
.LBB0_227:
	s_or_saveexec_b64 s[78:79], s[78:79]
	v_lshlrev_b32_e32 v90, 1, v64
	s_xor_b64 exec, exec, s[78:79]
	s_cbranch_execz .LBB0_229
	v_mov_b32_e32 v91, v189
	v_cvt_pk_bf16_f32 v33, v37, s0
	v_lshl_add_u64 v[38:39], v[34:35], 0, v[90:91]
	ds_write_b16 v222, v33 offset:36
.LBB0_229:
	s_or_b64 exec, exec, s[78:79]
	v_mul_f32_e64 v33, v69, |v36|
	v_mul_f32_e32 v33, 0x3fb8aa3b, v33
	v_exp_f32_e32 v33, v33
	s_nop 0
	v_mul_f32_e32 v37, v33, v11
	v_and_b32_e32 v11, 0x7fffffff, v37
	s_and_saveexec_b64 s[78:79], s[6:7]
	s_xor_b64 s[78:79], exec, s[78:79]
	s_cbranch_execz .LBB0_231
	v_mov_b32_e32 v33, v189
	v_lshl_add_u64 v[38:39], v[34:35], 0, v[32:33]
	v_add_co_u32_e32 v38, vcc, 0x4000, v38
	v_cvt_pk_bf16_f32 v33, v37, s0
	s_nop 0
	v_addc_co_u32_e32 v39, vcc, 0, v39, vcc
	ds_write_b16 v222, v33 offset:38
.LBB0_231:
	s_or_saveexec_b64 s[78:79], s[78:79]
	v_lshlrev_b32_e32 v88, 1, v66
	s_xor_b64 exec, exec, s[78:79]
	s_cbranch_execz .LBB0_233
	v_mov_b32_e32 v89, v189
	v_cvt_pk_bf16_f32 v33, v37, s0
	v_lshl_add_u64 v[38:39], v[34:35], 0, v[88:89]
	ds_write_b16 v222, v33 offset:38
.LBB0_233:
	s_or_b64 exec, exec, s[78:79]
	v_mul_f32_e64 v33, v71, |v36|
	v_mul_f32_e32 v33, 0x3fb8aa3b, v33
	v_exp_f32_e32 v33, v33
	s_nop 0
	v_mul_f32_e32 v37, v33, v12
	v_and_b32_e32 v12, 0x7fffffff, v37
	s_and_saveexec_b64 s[78:79], s[6:7]
	s_xor_b64 s[78:79], exec, s[78:79]
	s_cbranch_execz .LBB0_235
	v_mov_b32_e32 v33, v189
	v_lshl_add_u64 v[38:39], v[34:35], 0, v[32:33]
	v_add_co_u32_e32 v38, vcc, 0x4000, v38
	v_cvt_pk_bf16_f32 v33, v37, s0
	s_nop 0
	v_addc_co_u32_e32 v39, vcc, 0, v39, vcc
	ds_write_b16 v222, v33 offset:48
.LBB0_235:
	s_or_saveexec_b64 s[78:79], s[78:79]
	v_lshlrev_b32_e32 v86, 1, v68
	s_xor_b64 exec, exec, s[78:79]
	s_cbranch_execz .LBB0_237
	v_mov_b32_e32 v87, v189
	v_cvt_pk_bf16_f32 v33, v37, s0
	v_lshl_add_u64 v[38:39], v[34:35], 0, v[86:87]
	ds_write_b16 v222, v33 offset:48
.LBB0_237:
	s_or_b64 exec, exec, s[78:79]
	v_mul_f32_e64 v33, v73, |v36|
	v_mul_f32_e32 v33, 0x3fb8aa3b, v33
	v_exp_f32_e32 v33, v33
	s_nop 0
	v_mul_f32_e32 v37, v33, v13
	v_and_b32_e32 v13, 0x7fffffff, v37
	s_and_saveexec_b64 s[78:79], s[6:7]
	s_xor_b64 s[78:79], exec, s[78:79]
	s_cbranch_execz .LBB0_239
	v_mov_b32_e32 v33, v189
	v_lshl_add_u64 v[38:39], v[34:35], 0, v[32:33]
	v_add_co_u32_e32 v38, vcc, 0x4000, v38
	v_cvt_pk_bf16_f32 v33, v37, s0
	s_nop 0
	v_addc_co_u32_e32 v39, vcc, 0, v39, vcc
	ds_write_b16 v222, v33 offset:50
.LBB0_239:
	s_or_saveexec_b64 s[78:79], s[78:79]
	v_lshlrev_b32_e32 v84, 1, v70
	s_xor_b64 exec, exec, s[78:79]
	s_cbranch_execz .LBB0_241
	v_mov_b32_e32 v85, v189
	v_cvt_pk_bf16_f32 v33, v37, s0
	v_lshl_add_u64 v[38:39], v[34:35], 0, v[84:85]
	ds_write_b16 v222, v33 offset:50
.LBB0_241:
	s_or_b64 exec, exec, s[78:79]
	v_mul_f32_e64 v33, v75, |v36|
	v_mul_f32_e32 v33, 0x3fb8aa3b, v33
	v_exp_f32_e32 v33, v33
	s_nop 0
	v_mul_f32_e32 v37, v33, v14
	v_and_b32_e32 v14, 0x7fffffff, v37
	s_and_saveexec_b64 s[78:79], s[6:7]
	s_xor_b64 s[78:79], exec, s[78:79]
	s_cbranch_execz .LBB0_243
	v_mov_b32_e32 v33, v189
	v_lshl_add_u64 v[38:39], v[34:35], 0, v[32:33]
	v_add_co_u32_e32 v38, vcc, 0x4000, v38
	v_cvt_pk_bf16_f32 v33, v37, s0
	s_nop 0
	v_addc_co_u32_e32 v39, vcc, 0, v39, vcc
	ds_write_b16 v222, v33 offset:52
.LBB0_243:
	s_or_saveexec_b64 s[78:79], s[78:79]
	v_lshlrev_b32_e32 v38, 1, v72
	s_xor_b64 exec, exec, s[78:79]
	s_cbranch_execz .LBB0_245
	v_mov_b32_e32 v39, v189
	v_cvt_pk_bf16_f32 v33, v37, s0
	v_lshl_add_u64 v[146:147], v[34:35], 0, v[38:39]
	ds_write_b16 v222, v33 offset:52

; #define MFMA(a, b, c) __builtin_amdgcn_mfma_f32_32x32x16_bf16((a), (b), (c), 0, 0, 0)
; DI u16 f2bf(float a) { return (u16)(pack2(a, 0.f) & 0xffffu); }
; DI int crow(int reg, int g) { return (reg & 3) + 8 * (reg >> 2) + 4 * g; }
; DI f32x16 zero16() { f32x16 z; for (int i = 0; i < 16; ++i) z[i] = 0.f; return z; }
; DI void filter_tile(const P& p, int l, int tile, char* smem) {
;     ...
; #pragma unroll
;     for (int u = 0; u < 2; ++u) {
;       const int col = wave * 256 + (nb + u) * 32 + li;
;       f32x16 acc = zero16();
; #pragma unroll
;       for (int ks = 0; ks < 4; ++ks) acc = MFMA(af[ks], __builtin_bit_cast(bf16x8, bw[u][ks]), acc);
;       const int j = col >> 9, c = col & 511;
;       const int order = j & 1;
;       const bool fwd = j < 2;
;       const float delta = fabsf(min_decay + (float)c * ((max_decay - min_decay) / 511.0f));
;       u16* tb = p.Tb + (size_t)(order * 512 + c) * 16384;
;       float asum = 0.f;
; #pragma unroll
;       for (int reg = 0; reg < 16; ++reg) {
;         const int m = m0 + crow(reg, g);
;         const float t = (float)m / 8191.0f;
;         const float v = acc[reg] * __expf(-t * delta);
;         if (fwd) { tb[8192 - m] = f2bf(v); asum += fabsf(v); }
;         else if (m >= 1) { tb[8192 + m] = f2bf(v); asum += fabsf(v); }
;       }
;       if (fwd && tile == 0 && g == 0) tb[0] = 0;
;       asum += __shfl_xor(asum, 32);
;       if (g == 0) p.npart[(size_t)tile * 2048 + col] = asum;
.LBB0_249:
	s_or_b64 exec, exec, s[78:79]
	s_waitcnt lgkmcnt(0)
	ds_read_u16 v224, v223 offset:0
	ds_read_u16 v225, v223 offset:136
	ds_read_u16 v226, v223 offset:272
	ds_read_u16 v227, v223 offset:408
	ds_read_u16 v228, v223 offset:544
	ds_read_u16 v229, v223 offset:680
	ds_read_u16 v230, v223 offset:816
	ds_read_u16 v231, v223 offset:952
	ds_read_u16 v232, v223 offset:1088
	ds_read_u16 v233, v223 offset:1224
	ds_read_u16 v234, v223 offset:1360
	ds_read_u16 v235, v223 offset:1496
	ds_read_u16 v236, v223 offset:1632
	ds_read_u16 v237, v223 offset:1768
	ds_read_u16 v238, v223 offset:1904
	ds_read_u16 v239, v223 offset:2040
	v_readfirstlane_b32 s78, v34
	v_readfirstlane_b32 s79, v35
	v_mov_b32_e32 v246, v240
	v_and_b32_e32 v247, 0x7fff, v240
	v_cmp_eq_u32_e32 vcc, 0x4000, v247
	s_nop 1
	s_and_b64 s[80:81], vcc, s[6:7]
	s_andn2_b64 exec, exec, s[80:81]
	s_waitcnt lgkmcnt(0)
	global_store_short v246, v224, s[78:79]
	v_add_u32_e32 v246, 0x10000, v246
	global_store_short v246, v225, s[78:79]
	v_add_u32_e32 v246, 0x10000, v246
	global_store_short v246, v226, s[78:79]
	v_add_u32_e32 v246, 0x10000, v246
	global_store_short v246, v227, s[78:79]
	v_add_u32_e32 v246, 0x10000, v246
	global_store_short v246, v228, s[78:79]
	v_add_u32_e32 v246, 0x10000, v246
	global_store_short v246, v229, s[78:79]
	v_add_u32_e32 v246, 0x10000, v246
	global_store_short v246, v230, s[78:79]
	v_add_u32_e32 v246, 0x10000, v246
	global_store_short v246, v231, s[78:79]
	v_add_u32_e32 v246, 0x10000, v246
	global_store_short v246, v232, s[78:79]
	v_add_u32_e32 v246, 0x10000, v246
	global_store_short v246, v233, s[78:79]
	v_add_u32_e32 v246, 0x10000, v246
	global_store_short v246, v234, s[78:79]
	v_add_u32_e32 v246, 0x10000, v246
	global_store_short v246, v235, s[78:79]
	v_add_u32_e32 v246, 0x10000, v246
	global_store_short v246, v236, s[78:79]
	v_add_u32_e32 v246, 0x10000, v246
	global_store_short v246, v237, s[78:79]
	v_add_u32_e32 v246, 0x10000, v246
	global_store_short v246, v238, s[78:79]
	v_add_u32_e32 v246, 0x10000, v246
	global_store_short v246, v239, s[78:79]
	s_mov_b64 exec, -1
	v_add_f32_e32 v0, v0, v1
	v_add_f32_e32 v0, v0, v2
	v_add_f32_e32 v0, v0, v3
	v_add_f32_e32 v0, v0, v4
	v_add_f32_e32 v0, v0, v5
	v_add_f32_e32 v0, v0, v6
	v_add_f32_e32 v0, v0, v7
	v_add_f32_e32 v0, v0, v8
	v_add_f32_e32 v0, v0, v9
	v_add_f32_e32 v0, v0, v10
	v_add_f32_e32 v0, v0, v11
	v_add_f32_e32 v0, v0, v12
	v_add_f32_e32 v0, v0, v13
	v_add_f32_e32 v0, v0, v14
	v_add_f32_e32 v0, v0, v15
	ds_bpermute_b32 v1, v45, v0
	v_lshl_add_u64 v[34:35], v[76:77], 2, s[76:77]
	s_and_saveexec_b64 s[78:79], s[8:9]
	s_cbranch_execz .LBB0_251
	s_waitcnt lgkmcnt(0)
	v_add_f32_e32 v0, v0, v1
	global_store_dword v[34:35], v0, off
.LBB0_251:
	s_or_b64 exec, exec, s[78:79]
	s_waitcnt vmcnt(30)
	v_cvt_pk_bf16_f32 v0, v112, v113
	s_waitcnt vmcnt(28) lgkmcnt(0)
	v_cvt_pk_bf16_f32 v1, v115, v116
	s_waitcnt vmcnt(26)
	v_cvt_pk_bf16_f32 v2, v117, v118
	s_waitcnt vmcnt(24)
	v_cvt_pk_bf16_f32 v3, v119, v120
	s_waitcnt vmcnt(22)
	v_cvt_pk_bf16_f32 v116, v121, v122
	s_waitcnt vmcnt(19)
	v_cvt_pk_bf16_f32 v117, v123, v124
	v_mfma_f32_32x32x16_bf16 v[0:15], v[16:19], v[0:3], 0
	s_waitcnt vmcnt(17)
	v_cvt_pk_bf16_f32 v118, v125, v126
	s_waitcnt vmcnt(15)
	v_cvt_pk_bf16_f32 v119, v127, v128
	s_waitcnt vmcnt(13)
	v_cvt_pk_bf16_f32 v120, v129, v130
	s_waitcnt vmcnt(11)
	v_cvt_pk_bf16_f32 v121, v131, v132
	s_waitcnt vmcnt(9)
	v_cvt_pk_bf16_f32 v122, v133, v134
	s_waitcnt vmcnt(7)
	v_cvt_pk_bf16_f32 v123, v135, v136
	v_add_u32_e32 v33, 32, v76
	v_mfma_f32_32x32x16_bf16 v[0:15], v[20:23], v[116:119], v[0:15]
	v_and_b32_e32 v33, 0x1ff, v33
	v_cvt_f32_u32_e32 v37, v33
	s_waitcnt vmcnt(6)
	v_cvt_pk_bf16_f32 v116, v137, v138
	s_waitcnt vmcnt(4)
	v_cvt_pk_bf16_f32 v117, v139, v141
	s_waitcnt vmcnt(2)
	v_cvt_pk_bf16_f32 v118, v140, v142
	s_waitcnt vmcnt(0)
	v_cvt_pk_bf16_f32 v119, v143, v144
	v_fmamk_f32 v37, v37, 0xbcc4df2d, v201
	v_mfma_f32_32x32x16_bf16 v[0:15], v[24:27], v[120:123], v[0:15]
	v_mul_f32_e64 v39, v47, |v37|
	v_mul_f32_e32 v39, 0x3fb8aa3b, v39
	v_exp_f32_e32 v39, v39
	v_or_b32_e32 v33, v33, v43
	v_lshlrev_b32_e32 v188, 15, v33
	v_lshl_add_u64 v[112:113], s[44:45], 0, v[188:189]
	v_mfma_f32_32x32x16_bf16 v[0:15], v[28:31], v[116:119], v[0:15]
	s_nop 11
	v_mul_f32_e32 v39, v39, v0
	v_and_b32_e32 v0, 0x7fffffff, v39
	s_and_saveexec_b64 s[78:79], s[6:7]
	s_xor_b64 s[78:79], exec, s[78:79]
	s_cbranch_execz .LBB0_255
	v_mov_b32_e32 v0, 0
	s_and_saveexec_b64 s[80:81], s[10:11]
	s_cbranch_execz .LBB0_254
	v_mov_b32_e32 v33, v189
	v_lshl_add_u64 v[110:111], v[112:113], 0, v[32:33]
	v_add_co_u32_e32 v110, vcc, 0x4000, v110
	v_and_b32_e32 v0, 0x7fffffff, v39
	v_cvt_pk_bf16_f32 v33, v39, s0
	v_addc_co_u32_e32 v111, vcc, 0, v111, vcc
	ds_write_b16 v222, v33 offset:0

; DI u16 f2bf(float a) { return (u16)(pack2(a, 0.f) & 0xffffu); }
; DI int crow(int reg, int g) { return (reg & 3) + 8 * (reg >> 2) + 4 * g; }
; DI void filter_tile(const P& p, int l, int tile, char* smem) {
;     ...
; #pragma unroll
;       for (int reg = 0; reg < 16; ++reg) {
;         const int m = m0 + crow(reg, g);
;         const float t = (float)m / 8191.0f;
;         const float v = acc[reg] * __expf(-t * delta);
;         if (fwd) { tb[8192 - m] = f2bf(v); asum += fabsf(v); }
;         else if (m >= 1) { tb[8192 + m] = f2bf(v); asum += fabsf(v); }
;       }
.LBB0_255:
	s_andn2_saveexec_b64 s[78:79], s[78:79]
	s_cbranch_execz .LBB0_257
	v_mov_b32_e32 v111, v189
	v_cvt_pk_bf16_f32 v33, v39, s0
	v_lshl_add_u64 v[110:111], v[112:113], 0, v[110:111]
	ds_write_b16 v222, v33 offset:0
.LBB0_257:
	s_or_b64 exec, exec, s[78:79]
	v_mul_f32_e64 v33, v49, |v37|
	v_mul_f32_e32 v33, 0x3fb8aa3b, v33
	v_exp_f32_e32 v33, v33
	s_nop 0
	v_mul_f32_e32 v39, v33, v1
	v_and_b32_e32 v1, 0x7fffffff, v39
	s_and_saveexec_b64 s[78:79], s[6:7]
	s_xor_b64 s[78:79], exec, s[78:79]
	s_cbranch_execz .LBB0_259
	v_mov_b32_e32 v33, v189
	v_lshl_add_u64 v[108:109], v[112:113], 0, v[32:33]
	v_add_co_u32_e32 v108, vcc, 0x4000, v108
	v_cvt_pk_bf16_f32 v33, v39, s0
	s_nop 0
	v_addc_co_u32_e32 v109, vcc, 0, v109, vcc
	ds_write_b16 v222, v33 offset:2
.LBB0_259:
	s_andn2_saveexec_b64 s[78:79], s[78:79]
	s_cbranch_execz .LBB0_261
	v_mov_b32_e32 v109, v189
	v_cvt_pk_bf16_f32 v33, v39, s0
	v_lshl_add_u64 v[108:109], v[112:113], 0, v[108:109]
	ds_write_b16 v222, v33 offset:2
.LBB0_261:
	s_or_b64 exec, exec, s[78:79]
	v_mul_f32_e64 v33, v51, |v37|
	v_mul_f32_e32 v33, 0x3fb8aa3b, v33
	v_exp_f32_e32 v33, v33
	s_nop 0
	v_mul_f32_e32 v39, v33, v2
	v_and_b32_e32 v2, 0x7fffffff, v39
	s_and_saveexec_b64 s[78:79], s[6:7]
	s_xor_b64 s[78:79], exec, s[78:79]
	s_cbranch_execz .LBB0_263
	v_mov_b32_e32 v33, v189
	v_lshl_add_u64 v[106:107], v[112:113], 0, v[32:33]
	v_add_co_u32_e32 v106, vcc, 0x4000, v106
	v_cvt_pk_bf16_f32 v33, v39, s0
	s_nop 0
	v_addc_co_u32_e32 v107, vcc, 0, v107, vcc
	ds_write_b16 v222, v33 offset:4
.LBB0_263:
	s_andn2_saveexec_b64 s[78:79], s[78:79]
	s_cbranch_execz .LBB0_265
	v_mov_b32_e32 v107, v189
	v_cvt_pk_bf16_f32 v33, v39, s0
	v_lshl_add_u64 v[106:107], v[112:113], 0, v[106:107]
	ds_write_b16 v222, v33 offset:4
.LBB0_265:
	s_or_b64 exec, exec, s[78:79]
	v_mul_f32_e64 v33, v53, |v37|
	v_mul_f32_e32 v33, 0x3fb8aa3b, v33
	v_exp_f32_e32 v33, v33
	s_nop 0
	v_mul_f32_e32 v39, v33, v3
	v_and_b32_e32 v3, 0x7fffffff, v39
	s_and_saveexec_b64 s[78:79], s[6:7]
	s_xor_b64 s[78:79], exec, s[78:79]
	s_cbranch_execz .LBB0_267
	v_mov_b32_e32 v33, v189
	v_lshl_add_u64 v[104:105], v[112:113], 0, v[32:33]
	v_add_co_u32_e32 v104, vcc, 0x4000, v104
	v_cvt_pk_bf16_f32 v33, v39, s0
	s_nop 0
	v_addc_co_u32_e32 v105, vcc, 0, v105, vcc
	ds_write_b16 v222, v33 offset:6
.LBB0_267:
	s_andn2_saveexec_b64 s[78:79], s[78:79]
	s_cbranch_execz .LBB0_269
	v_mov_b32_e32 v105, v189
	v_cvt_pk_bf16_f32 v33, v39, s0
	v_lshl_add_u64 v[104:105], v[112:113], 0, v[104:105]
	ds_write_b16 v222, v33 offset:6
.LBB0_269:
	s_or_b64 exec, exec, s[78:79]
	v_mul_f32_e64 v33, v55, |v37|
	v_mul_f32_e32 v33, 0x3fb8aa3b, v33
	v_exp_f32_e32 v33, v33
	s_nop 0
	v_mul_f32_e32 v39, v33, v4
	v_and_b32_e32 v4, 0x7fffffff, v39
	s_and_saveexec_b64 s[78:79], s[6:7]
	s_xor_b64 s[78:79], exec, s[78:79]
	s_cbranch_execz .LBB0_271
	v_mov_b32_e32 v33, v189
	v_lshl_add_u64 v[102:103], v[112:113], 0, v[32:33]
	v_add_co_u32_e32 v102, vcc, 0x4000, v102
	v_cvt_pk_bf16_f32 v33, v39, s0
	s_nop 0
	v_addc_co_u32_e32 v103, vcc, 0, v103, vcc
	ds_write_b16 v222, v33 offset:16
.LBB0_271:
	s_andn2_saveexec_b64 s[78:79], s[78:79]
	s_cbranch_execz .LBB0_273
	v_mov_b32_e32 v103, v189
	v_cvt_pk_bf16_f32 v33, v39, s0
	v_lshl_add_u64 v[102:103], v[112:113], 0, v[102:103]
	ds_write_b16 v222, v33 offset:16
.LBB0_273:
	s_or_b64 exec, exec, s[78:79]
	v_mul_f32_e64 v33, v57, |v37|
	v_mul_f32_e32 v33, 0x3fb8aa3b, v33
	v_exp_f32_e32 v33, v33
	s_nop 0
	v_mul_f32_e32 v39, v33, v5
	v_and_b32_e32 v5, 0x7fffffff, v39
	s_and_saveexec_b64 s[78:79], s[6:7]
	s_xor_b64 s[78:79], exec, s[78:79]
	s_cbranch_execz .LBB0_275
	v_mov_b32_e32 v33, v189
	v_lshl_add_u64 v[100:101], v[112:113], 0, v[32:33]
	v_add_co_u32_e32 v100, vcc, 0x4000, v100
	v_cvt_pk_bf16_f32 v33, v39, s0
	s_nop 0
	v_addc_co_u32_e32 v101, vcc, 0, v101, vcc
	ds_write_b16 v222, v33 offset:18
.LBB0_275:
	s_andn2_saveexec_b64 s[78:79], s[78:79]
	s_cbranch_execz .LBB0_277
	v_mov_b32_e32 v101, v189
	v_cvt_pk_bf16_f32 v33, v39, s0
	v_lshl_add_u64 v[100:101], v[112:113], 0, v[100:101]
	ds_write_b16 v222, v33 offset:18
.LBB0_277:
	s_or_b64 exec, exec, s[78:79]
	v_mul_f32_e64 v33, v59, |v37|
	v_mul_f32_e32 v33, 0x3fb8aa3b, v33
	v_exp_f32_e32 v33, v33
	s_nop 0
	v_mul_f32_e32 v39, v33, v6
	v_and_b32_e32 v6, 0x7fffffff, v39
	s_and_saveexec_b64 s[78:79], s[6:7]
	s_xor_b64 s[78:79], exec, s[78:79]
	s_cbranch_execz .LBB0_279
	v_mov_b32_e32 v33, v189
	v_lshl_add_u64 v[98:99], v[112:113], 0, v[32:33]
	v_add_co_u32_e32 v98, vcc, 0x4000, v98
	v_cvt_pk_bf16_f32 v33, v39, s0
	s_nop 0
	v_addc_co_u32_e32 v99, vcc, 0, v99, vcc
	ds_write_b16 v222, v33 offset:20
.LBB0_279:
	s_andn2_saveexec_b64 s[78:79], s[78:79]
	s_cbranch_execz .LBB0_281
	v_mov_b32_e32 v99, v189
	v_cvt_pk_bf16_f32 v33, v39, s0
	v_lshl_add_u64 v[98:99], v[112:113], 0, v[98:99]
	ds_write_b16 v222, v33 offset:20
.LBB0_281:
	s_or_b64 exec, exec, s[78:79]
	v_mul_f32_e64 v33, v61, |v37|
	v_mul_f32_e32 v33, 0x3fb8aa3b, v33
	v_exp_f32_e32 v33, v33
	s_nop 0
	v_mul_f32_e32 v39, v33, v7
	v_and_b32_e32 v7, 0x7fffffff, v39
	s_and_saveexec_b64 s[78:79], s[6:7]
	s_xor_b64 s[78:79], exec, s[78:79]
	s_cbranch_execz .LBB0_283
	v_mov_b32_e32 v33, v189
	v_lshl_add_u64 v[96:97], v[112:113], 0, v[32:33]
	v_add_co_u32_e32 v96, vcc, 0x4000, v96
	v_cvt_pk_bf16_f32 v33, v39, s0
	s_nop 0
	v_addc_co_u32_e32 v97, vcc, 0, v97, vcc
	ds_write_b16 v222, v33 offset:22
; DI u16 f2bf(float a) { return (u16)(pack2(a, 0.f) & 0xffffu); }
; DI int crow(int reg, int g) { return (reg & 3) + 8 * (reg >> 2) + 4 * g; }
; DI void filter_tile(const P& p, int l, int tile, char* smem) {
;     ...
; #pragma unroll
;       for (int reg = 0; reg < 16; ++reg) {
;         const int m = m0 + crow(reg, g);
;         const float t = (float)m / 8191.0f;
;         const float v = acc[reg] * __expf(-t * delta);
;         if (fwd) { tb[8192 - m] = f2bf(v); asum += fabsf(v); }
;         else if (m >= 1) { tb[8192 + m] = f2bf(v); asum += fabsf(v); }
;       }
.LBB0_283:
	s_andn2_saveexec_b64 s[78:79], s[78:79]
	s_cbranch_execz .LBB0_285
	v_mov_b32_e32 v97, v189
	v_cvt_pk_bf16_f32 v33, v39, s0
	v_lshl_add_u64 v[96:97], v[112:113], 0, v[96:97]
	ds_write_b16 v222, v33 offset:22
.LBB0_285:
	s_or_b64 exec, exec, s[78:79]
	v_mul_f32_e64 v33, v63, |v37|
	v_mul_f32_e32 v33, 0x3fb8aa3b, v33
	v_exp_f32_e32 v33, v33
	s_nop 0
	v_mul_f32_e32 v39, v33, v8
	v_and_b32_e32 v8, 0x7fffffff, v39
	s_and_saveexec_b64 s[78:79], s[6:7]
	s_xor_b64 s[78:79], exec, s[78:79]
	s_cbranch_execz .LBB0_287
	v_mov_b32_e32 v33, v189
	v_lshl_add_u64 v[94:95], v[112:113], 0, v[32:33]
	v_add_co_u32_e32 v94, vcc, 0x4000, v94
	v_cvt_pk_bf16_f32 v33, v39, s0
	s_nop 0
	v_addc_co_u32_e32 v95, vcc, 0, v95, vcc
	ds_write_b16 v222, v33 offset:32
.LBB0_287:
	s_andn2_saveexec_b64 s[78:79], s[78:79]
	s_cbranch_execz .LBB0_289
	v_mov_b32_e32 v95, v189
	v_cvt_pk_bf16_f32 v33, v39, s0
	v_lshl_add_u64 v[94:95], v[112:113], 0, v[94:95]
	ds_write_b16 v222, v33 offset:32
.LBB0_289:
	s_or_b64 exec, exec, s[78:79]
	v_mul_f32_e64 v33, v65, |v37|
	v_mul_f32_e32 v33, 0x3fb8aa3b, v33
	v_exp_f32_e32 v33, v33
	s_nop 0
	v_mul_f32_e32 v39, v33, v9
	v_and_b32_e32 v9, 0x7fffffff, v39
	s_and_saveexec_b64 s[78:79], s[6:7]
	s_xor_b64 s[78:79], exec, s[78:79]
	s_cbranch_execz .LBB0_291
	v_mov_b32_e32 v33, v189
	v_lshl_add_u64 v[92:93], v[112:113], 0, v[32:33]
	v_add_co_u32_e32 v92, vcc, 0x4000, v92
	v_cvt_pk_bf16_f32 v33, v39, s0
	s_nop 0
	v_addc_co_u32_e32 v93, vcc, 0, v93, vcc
	ds_write_b16 v222, v33 offset:34
.LBB0_291:
	s_andn2_saveexec_b64 s[78:79], s[78:79]
	s_cbranch_execz .LBB0_293
	v_mov_b32_e32 v93, v189
	v_cvt_pk_bf16_f32 v33, v39, s0
	v_lshl_add_u64 v[92:93], v[112:113], 0, v[92:93]
	ds_write_b16 v222, v33 offset:34
.LBB0_293:
	s_or_b64 exec, exec, s[78:79]
	v_mul_f32_e64 v33, v67, |v37|
	v_mul_f32_e32 v33, 0x3fb8aa3b, v33
	v_exp_f32_e32 v33, v33
	s_nop 0
	v_mul_f32_e32 v39, v33, v10
	v_and_b32_e32 v10, 0x7fffffff, v39
	s_and_saveexec_b64 s[78:79], s[6:7]
	s_xor_b64 s[78:79], exec, s[78:79]
	s_cbranch_execz .LBB0_295
	v_mov_b32_e32 v33, v189
	v_lshl_add_u64 v[90:91], v[112:113], 0, v[32:33]
	v_add_co_u32_e32 v90, vcc, 0x4000, v90
	v_cvt_pk_bf16_f32 v33, v39, s0
	s_nop 0
	v_addc_co_u32_e32 v91, vcc, 0, v91, vcc
	ds_write_b16 v222, v33 offset:36
.LBB0_295:
	s_andn2_saveexec_b64 s[78:79], s[78:79]
	s_cbranch_execz .LBB0_297
	v_mov_b32_e32 v91, v189
	v_cvt_pk_bf16_f32 v33, v39, s0
	v_lshl_add_u64 v[90:91], v[112:113], 0, v[90:91]
	ds_write_b16 v222, v33 offset:36
.LBB0_297:
	s_or_b64 exec, exec, s[78:79]
	v_mul_f32_e64 v33, v69, |v37|
	v_mul_f32_e32 v33, 0x3fb8aa3b, v33
	v_exp_f32_e32 v33, v33
	s_nop 0
	v_mul_f32_e32 v39, v33, v11
	v_and_b32_e32 v11, 0x7fffffff, v39
	s_and_saveexec_b64 s[78:79], s[6:7]
	s_xor_b64 s[78:79], exec, s[78:79]
	s_cbranch_execz .LBB0_299
	v_mov_b32_e32 v33, v189
	v_lshl_add_u64 v[88:89], v[112:113], 0, v[32:33]
	v_add_co_u32_e32 v88, vcc, 0x4000, v88
	v_cvt_pk_bf16_f32 v33, v39, s0
	s_nop 0
	v_addc_co_u32_e32 v89, vcc, 0, v89, vcc
	ds_write_b16 v222, v33 offset:38
.LBB0_299:
	s_andn2_saveexec_b64 s[78:79], s[78:79]
	s_cbranch_execz .LBB0_301
	v_mov_b32_e32 v89, v189
	v_cvt_pk_bf16_f32 v33, v39, s0
	v_lshl_add_u64 v[88:89], v[112:113], 0, v[88:89]
	ds_write_b16 v222, v33 offset:38
.LBB0_301:
	s_or_b64 exec, exec, s[78:79]
	v_mul_f32_e64 v33, v71, |v37|
	v_mul_f32_e32 v33, 0x3fb8aa3b, v33
	v_exp_f32_e32 v33, v33
	s_nop 0
	v_mul_f32_e32 v39, v33, v12
	v_and_b32_e32 v12, 0x7fffffff, v39
	s_and_saveexec_b64 s[78:79], s[6:7]
	s_xor_b64 s[78:79], exec, s[78:79]
	s_cbranch_execz .LBB0_303
	v_mov_b32_e32 v33, v189
	v_lshl_add_u64 v[86:87], v[112:113], 0, v[32:33]
	v_add_co_u32_e32 v86, vcc, 0x4000, v86
	v_cvt_pk_bf16_f32 v33, v39, s0
	s_nop 0
	v_addc_co_u32_e32 v87, vcc, 0, v87, vcc
	ds_write_b16 v222, v33 offset:48
.LBB0_303:
	s_andn2_saveexec_b64 s[78:79], s[78:79]
	s_cbranch_execz .LBB0_305
	v_mov_b32_e32 v87, v189
	v_cvt_pk_bf16_f32 v33, v39, s0
	v_lshl_add_u64 v[86:87], v[112:113], 0, v[86:87]
	ds_write_b16 v222, v33 offset:48
.LBB0_305:
	s_or_b64 exec, exec, s[78:79]
	v_mul_f32_e64 v33, v73, |v37|
	v_mul_f32_e32 v33, 0x3fb8aa3b, v33
	v_exp_f32_e32 v33, v33
	s_nop 0
	v_mul_f32_e32 v39, v33, v13
	v_and_b32_e32 v13, 0x7fffffff, v39
	s_and_saveexec_b64 s[78:79], s[6:7]
	s_xor_b64 s[78:79], exec, s[78:79]
	s_cbranch_execz .LBB0_307
	v_mov_b32_e32 v33, v189
	v_lshl_add_u64 v[84:85], v[112:113], 0, v[32:33]
	v_add_co_u32_e32 v84, vcc, 0x4000, v84
	v_cvt_pk_bf16_f32 v33, v39, s0
	s_nop 0
	v_addc_co_u32_e32 v85, vcc, 0, v85, vcc
	ds_write_b16 v222, v33 offset:50
.LBB0_307:
	s_andn2_saveexec_b64 s[78:79], s[78:79]
	s_cbranch_execz .LBB0_309
	v_mov_b32_e32 v85, v189
	v_cvt_pk_bf16_f32 v33, v39, s0
	v_lshl_add_u64 v[84:85], v[112:113], 0, v[84:85]
	ds_write_b16 v222, v33 offset:50
.LBB0_309:
	s_or_b64 exec, exec, s[78:79]
	v_mul_f32_e64 v33, v75, |v37|
	v_mul_f32_e32 v33, 0x3fb8aa3b, v33
	v_exp_f32_e32 v33, v33
	s_nop 0
	v_mul_f32_e32 v39, v33, v14
	v_and_b32_e32 v14, 0x7fffffff, v39
	s_and_saveexec_b64 s[78:79], s[6:7]
	s_xor_b64 s[78:79], exec, s[78:79]
	s_cbranch_execz .LBB0_311
	v_mov_b32_e32 v33, v189
	v_lshl_add_u64 v[84:85], v[112:113], 0, v[32:33]
	v_add_co_u32_e32 v38, vcc, 0x4000, v84
	v_cvt_pk_bf16_f32 v33, v39, s0
	s_nop 0
	v_addc_co_u32_e32 v39, vcc, 0, v85, vcc
	ds_write_b16 v222, v33 offset:52
.LBB0_311:
	s_andn2_saveexec_b64 s[78:79], s[78:79]
	s_cbranch_execz .LBB0_313
	v_cvt_pk_bf16_f32 v33, v39, s0
	v_mov_b32_e32 v39, v189
	v_lshl_add_u64 v[38:39], v[112:113], 0, v[38:39]
	ds_write_b16 v222, v33 offset:52

; DI u16 f2bf(float a) { return (u16)(pack2(a, 0.f) & 0xffffu); }
; DI void filter_tile(const P& p, int l, int tile, char* smem) {
;     ...
;         if (fwd) { tb[8192 - m] = f2bf(v); asum += fabsf(v); }
;         else if (m >= 1) { tb[8192 + m] = f2bf(v); asum += fabsf(v); }
;       }
;       if (fwd && tile == 0 && g == 0) tb[0] = 0;
;       asum += __shfl_xor(asum, 32);
;       if (g == 0) p.npart[(size_t)tile * 2048 + col] = asum;
.LBB0_317:
	s_or_b64 exec, exec, s[78:79]
	s_waitcnt lgkmcnt(0)
	ds_read_u16 v224, v223 offset:0
	ds_read_u16 v225, v223 offset:136
	ds_read_u16 v226, v223 offset:272
	ds_read_u16 v227, v223 offset:408
	ds_read_u16 v228, v223 offset:544
	ds_read_u16 v229, v223 offset:680
	ds_read_u16 v230, v223 offset:816
	ds_read_u16 v231, v223 offset:952
	ds_read_u16 v232, v223 offset:1088
	ds_read_u16 v233, v223 offset:1224
	ds_read_u16 v234, v223 offset:1360
	ds_read_u16 v235, v223 offset:1496
	ds_read_u16 v236, v223 offset:1632
	ds_read_u16 v237, v223 offset:1768
	ds_read_u16 v238, v223 offset:1904
	ds_read_u16 v239, v223 offset:2040
	v_readfirstlane_b32 s78, v112
	v_readfirstlane_b32 s79, v113
	v_mov_b32_e32 v246, v240
	v_and_b32_e32 v247, 0x7fff, v240
	v_cmp_eq_u32_e32 vcc, 0x4000, v247
	s_nop 1
	s_and_b64 s[80:81], vcc, s[6:7]
	s_andn2_b64 exec, exec, s[80:81]
	s_waitcnt lgkmcnt(0)
	global_store_short v246, v224, s[78:79]
	v_add_u32_e32 v246, 0x10000, v246
	global_store_short v246, v225, s[78:79]
	v_add_u32_e32 v246, 0x10000, v246
	global_store_short v246, v226, s[78:79]
	v_add_u32_e32 v246, 0x10000, v246
	global_store_short v246, v227, s[78:79]
	v_add_u32_e32 v246, 0x10000, v246
	global_store_short v246, v228, s[78:79]
	v_add_u32_e32 v246, 0x10000, v246
	global_store_short v246, v229, s[78:79]
	v_add_u32_e32 v246, 0x10000, v246
	global_store_short v246, v230, s[78:79]
	v_add_u32_e32 v246, 0x10000, v246
	global_store_short v246, v231, s[78:79]
	v_add_u32_e32 v246, 0x10000, v246
	global_store_short v246, v232, s[78:79]
	v_add_u32_e32 v246, 0x10000, v246
	global_store_short v246, v233, s[78:79]
	v_add_u32_e32 v246, 0x10000, v246
	global_store_short v246, v234, s[78:79]
	v_add_u32_e32 v246, 0x10000, v246
	global_store_short v246, v235, s[78:79]
	v_add_u32_e32 v246, 0x10000, v246
	global_store_short v246, v236, s[78:79]
	v_add_u32_e32 v246, 0x10000, v246
	global_store_short v246, v237, s[78:79]
	v_add_u32_e32 v246, 0x10000, v246
	global_store_short v246, v238, s[78:79]
	v_add_u32_e32 v246, 0x10000, v246
	global_store_short v246, v239, s[78:79]
	s_mov_b64 exec, -1
	v_add_f32_e32 v0, v0, v1
	v_add_f32_e32 v0, v0, v2
	v_add_f32_e32 v0, v0, v3
	v_add_f32_e32 v0, v0, v4
	v_add_f32_e32 v0, v0, v5
	v_add_f32_e32 v0, v0, v6
	v_add_f32_e32 v0, v0, v7
	v_add_f32_e32 v0, v0, v8
	v_add_f32_e32 v0, v0, v9
	v_add_f32_e32 v0, v0, v10
	v_add_f32_e32 v0, v0, v11
	v_add_f32_e32 v0, v0, v12
	v_add_f32_e32 v0, v0, v13
	v_add_f32_e32 v0, v0, v14
	v_add_f32_e32 v0, v0, v15
	ds_bpermute_b32 v1, v45, v0
	s_and_saveexec_b64 s[78:79], s[8:9]
	s_cbranch_execz .LBB0_182
	s_waitcnt lgkmcnt(0)
	v_add_f32_e32 v0, v0, v1
	global_store_dword v[34:35], v0, off offset:128
	s_branch .LBB0_182
.LBB0_319:
	v_mov_b32_e32 v33, v189
	v_lshl_add_u64 v[146:147], v[34:35], 0, v[32:33]
	v_add_co_u32_e32 v36, vcc, 0x4000, v146
	v_cvt_pk_bf16_f32 v33, v37, s0
	s_nop 0
	v_addc_co_u32_e32 v37, vcc, 0, v147, vcc
	ds_write_b16 v222, v33 offset:54
	s_or_saveexec_b64 s[78:79], s[78:79]
	v_lshlrev_b32_e32 v36, 1, v74
	s_xor_b64 exec, exec, s[78:79]
	s_cbranch_execz .LBB0_247
.LBB0_320:
	v_cvt_pk_bf16_f32 v33, v37, s0
	v_mov_b32_e32 v37, v189
	v_lshl_add_u64 v[146:147], v[34:35], 0, v[36:37]
	ds_write_b16 v222, v33 offset:54
	s_or_b64 exec, exec, s[78:79]
	s_and_saveexec_b64 s[78:79], s[74:75]
	s_cbranch_execnz .LBB0_248
	s_branch .LBB0_249
.LBB0_321:
	v_mov_b32_e32 v33, v189
	v_lshl_add_u64 v[32:33], v[112:113], 0, v[32:33]
	v_add_co_u32_e32 v32, vcc, 0x4000, v32
	v_cvt_pk_bf16_f32 v36, v37, s0
	s_nop 0
	v_addc_co_u32_e32 v33, vcc, 0, v33, vcc
	ds_write_b16 v222, v36 offset:54
	s_andn2_saveexec_b64 s[78:79], s[78:79]
	s_cbranch_execz .LBB0_315
.LBB0_322:
	v_cvt_pk_bf16_f32 v38, v37, s0
	v_mov_b32_e32 v37, v189
	v_lshl_add_u64 v[32:33], v[112:113], 0, v[36:37]
	ds_write_b16 v222, v38 offset:54
	s_or_b64 exec, exec, s[78:79]
	s_and_saveexec_b64 s[78:79], s[74:75]
	s_cbranch_execnz .LBB0_316
	s_branch .LBB0_317
